# fill_rstd_table (6 sites): 4 serialized iterations unrolled, all 16 stat loads issued before the first wait
# baseline (speedup 1.0000x reference)
; #define PG8_LAS __attribute__((address_space(3)))
;     __host__ __device__ __forceinline__ bool next(int i, Unit& u) const {
;         const long L = (long)i * G + c; if (L >= nwg) return false;
;         int wgid = (int)L; { const int q = nwg / NXCD, r = nwg % NXCD, xcd = wgid % NXCD, off = wgid / NXCD; wgid = (xcd < r ? xcd * (q + 1) : r * (q + 1) + (xcd - r) * q) + off; }
;         const int nig = WGM * nN, gid = wgid / nig, fm = gid * WGM, gsz = (nM - fm) < WGM ? (nM - fm) : WGM;
;         u.pm = fm + ((wgid % nig) % gsz); u.pn = (wgid % nig) / gsz; return true;
;     }
; __device__ __forceinline__ unsigned cvt_pk_bf16(float lo, float hi) { unsigned r; asm volatile("v_cvt_pk_bf16_f32 %0, %1, %2" : "=v"(r) : "v"(lo), "v"(hi)); return r; }
; __device__ __forceinline__ float row_rstd(const float* stats, int row) { const f32x4* sp = (const f32x4*)(stats + (size_t)row * 16); const f32x4 a = sp[0], b = sp[1], c = sp[2], d = sp[3];
;     const float s = ((a[0] + a[1]) + (a[2] + a[3])) + ((b[0] + b[1]) + (b[2] + b[3])) + ((c[0] + c[1]) + (c[2] + c[3])) + ((d[0] + d[1]) + (d[2] + d[3])); return rsqrtf(s * (1.0f / 1024.0f) + 1e-6f); }
; template <class Sched> __device__ __forceinline__ void fill_rstd_table(PG8_LAS float* rsL, const float* stats, const Sched& S, int tid) {
;     Unit u; int n = 0; while (n < 8 && S.next(n, u)) ++n;
;     for (int idx = tid; idx < n * 256; idx += 512) { S.next(idx >> 8, u); rsL[idx] = row_rstd(stats, u.pm * BM + (idx & 255)); }
;     asm volatile("s_waitcnt lgkmcnt(0)" ::: "memory"); __builtin_amdgcn_s_barrier(); asm volatile("" ::: "memory");
.LBB0_141:
	s_waitcnt lgkmcnt(0)
	s_add_u32 s18, s6, s10
	s_addc_u32 s19, s7, 0
	v_cmp_gt_i32_e32 vcc, s14, v136
	s_and_saveexec_b64 s[6:7], vcc
	s_cbranch_execz .LBB0_146
	s_add_u32 s8, s18, 0x400000
	v_lshl_add_u32 v0, v136, 2, 0
	s_addc_u32 s9, s19, 0
	v_and_b32_e32 v4, 0xff, v136
	v_add_u32_e32 v5, 0x22000, v0
	s_mov_b64 s[10:11], 0
	v_mov_b32_e32 v10, s12
	v_mov_b64_e32 v[0:1], s[20:21]
	s_mov_b64 s[12:13], 0x580
	s_movk_i32 s15, 0xb0
	s_mov_b32 s22, 0x2e8ba2e9
	v_mov_b32_e32 v6, 0x358637bd
	s_mov_b32 s23, 0x800000
	v_mov_b32_e32 v7, 0xb0
	v_mov_b32_e32 v8, 0xb1
	v_mov_b32_e32 v9, v136
	v_ashrrev_i32_e32 v2, 8, v9
	v_mad_i64_i32 v[2:3], s[4:5], v2, s57, v[0:1]
	v_cmp_gt_i64_e32 vcc, s[12:13], v[2:3]
	s_and_saveexec_b64 s[4:5], vcc
	s_cbranch_execz .Lfill0_skip0
	v_ashrrev_i32_e32 v3, 31, v2
	v_lshrrev_b32_e32 v3, 29, v3
	v_add_u32_e32 v3, v2, v3
	v_ashrrev_i32_e32 v10, 3, v3
	v_and_b32_e32 v3, -8, v3
	v_sub_u32_e32 v2, v2, v3
	v_cmp_gt_i32_e32 vcc, 0, v2
	s_nop 1
	v_cndmask_b32_e32 v3, v7, v8, vcc
	v_mul_lo_u32 v2, v2, v3
	v_add_u32_e32 v2, v2, v10
	v_mul_hi_i32 v3, v2, s22
	v_lshrrev_b32_e32 v10, 31, v3
	v_ashrrev_i32_e32 v3, 5, v3
	v_add_u32_e32 v3, v3, v10
	v_lshlrev_b32_e32 v10, 3, v3
	v_sub_u32_e32 v11, 64, v10
	v_min_i32_e32 v11, 8, v11
	v_sub_u32_e32 v12, 0, v11
	v_max_i32_e32 v11, v11, v12
	v_cvt_f32_u32_e32 v12, v11
	v_mul_lo_u32 v3, v3, s15
	v_sub_u32_e32 v2, v2, v3
	v_sub_u32_e32 v13, 0, v2
	v_rcp_iflag_f32_e32 v12, v12
	v_ashrrev_i32_e32 v3, 31, v2
	v_max_i32_e32 v2, v2, v13
	v_sub_u32_e32 v13, 0, v11
	v_mul_f32_e32 v12, 0x4f7ffffe, v12
	v_cvt_u32_f32_e32 v12, v12
	v_mul_lo_u32 v13, v13, v12
	v_mul_hi_u32 v13, v12, v13
	v_add_u32_e32 v12, v12, v13
	v_mul_hi_u32 v12, v2, v12
	v_mul_lo_u32 v12, v12, v11
	v_sub_u32_e32 v2, v2, v12
	v_sub_u32_e32 v12, v2, v11
	v_cmp_ge_u32_e32 vcc, v2, v11
	s_nop 1
	v_cndmask_b32_e32 v2, v2, v12, vcc
	v_sub_u32_e32 v12, v2, v11
	v_cmp_ge_u32_e32 vcc, v2, v11
	s_nop 1
	v_cndmask_b32_e32 v2, v2, v12, vcc
	v_xor_b32_e32 v2, v2, v3
	v_sub_u32_e32 v2, v2, v3
	v_add_u32_e32 v10, v10, v2
.Lfill0_skip0:
	s_or_b64 exec, exec, s[4:5]
	v_lshl_or_b32 v2, v10, 8, v4
	v_ashrrev_i32_e32 v3, 31, v2
	v_lshlrev_b64 v[2:3], 6, v[2:3]
	v_lshl_add_u64 v[2:3], s[8:9], 0, v[2:3]
	global_load_dwordx4 v[28:31], v[2:3], off
	global_load_dwordx4 v[32:35], v[2:3], off offset:16
	global_load_dwordx4 v[36:39], v[2:3], off offset:32
	global_load_dwordx4 v[40:43], v[2:3], off offset:48
	v_add_u32_e32 v9, 0x200, v9
	v_ashrrev_i32_e32 v2, 8, v9
	v_mad_i64_i32 v[2:3], s[4:5], v2, s57, v[0:1]
	v_cmp_gt_i64_e32 vcc, s[12:13], v[2:3]
	s_and_saveexec_b64 s[4:5], vcc
	s_cbranch_execz .Lfill0_skip1
	v_ashrrev_i32_e32 v3, 31, v2
	v_lshrrev_b32_e32 v3, 29, v3
	v_add_u32_e32 v3, v2, v3
	v_ashrrev_i32_e32 v10, 3, v3
	v_and_b32_e32 v3, -8, v3
	v_sub_u32_e32 v2, v2, v3
	v_cmp_gt_i32_e32 vcc, 0, v2
	s_nop 1
	v_cndmask_b32_e32 v3, v7, v8, vcc
	v_mul_lo_u32 v2, v2, v3
	v_add_u32_e32 v2, v2, v10
	v_mul_hi_i32 v3, v2, s22
	v_lshrrev_b32_e32 v10, 31, v3
	v_ashrrev_i32_e32 v3, 5, v3
	v_add_u32_e32 v3, v3, v10
	v_lshlrev_b32_e32 v10, 3, v3
	v_sub_u32_e32 v11, 64, v10
	v_min_i32_e32 v11, 8, v11
	v_sub_u32_e32 v12, 0, v11
	v_max_i32_e32 v11, v11, v12
	v_cvt_f32_u32_e32 v12, v11
	v_mul_lo_u32 v3, v3, s15
	v_sub_u32_e32 v2, v2, v3
	v_sub_u32_e32 v13, 0, v2
	v_rcp_iflag_f32_e32 v12, v12
	v_ashrrev_i32_e32 v3, 31, v2
	v_max_i32_e32 v2, v2, v13
	v_sub_u32_e32 v13, 0, v11
	v_mul_f32_e32 v12, 0x4f7ffffe, v12
	v_cvt_u32_f32_e32 v12, v12
	v_mul_lo_u32 v13, v13, v12
	v_mul_hi_u32 v13, v12, v13
	v_add_u32_e32 v12, v12, v13
	v_mul_hi_u32 v12, v2, v12
	v_mul_lo_u32 v12, v12, v11
	v_sub_u32_e32 v2, v2, v12
	v_sub_u32_e32 v12, v2, v11
	v_cmp_ge_u32_e32 vcc, v2, v11
	s_nop 1
	v_cndmask_b32_e32 v2, v2, v12, vcc
	v_sub_u32_e32 v12, v2, v11
	v_cmp_ge_u32_e32 vcc, v2, v11
	s_nop 1
	v_cndmask_b32_e32 v2, v2, v12, vcc
	v_xor_b32_e32 v2, v2, v3
	v_sub_u32_e32 v2, v2, v3
	v_add_u32_e32 v10, v10, v2
.Lfill0_skip1:
	s_or_b64 exec, exec, s[4:5]
	v_lshl_or_b32 v2, v10, 8, v4
	v_ashrrev_i32_e32 v3, 31, v2
	v_lshlrev_b64 v[2:3], 6, v[2:3]
	v_lshl_add_u64 v[2:3], s[8:9], 0, v[2:3]
	global_load_dwordx4 v[44:47], v[2:3], off
	global_load_dwordx4 v[48:51], v[2:3], off offset:16
	global_load_dwordx4 v[52:55], v[2:3], off offset:32
	global_load_dwordx4 v[56:59], v[2:3], off offset:48
	v_add_u32_e32 v9, 0x200, v9
	v_ashrrev_i32_e32 v2, 8, v9
	v_mad_i64_i32 v[2:3], s[4:5], v2, s57, v[0:1]
	v_cmp_gt_i64_e32 vcc, s[12:13], v[2:3]
	s_and_saveexec_b64 s[4:5], vcc
	s_cbranch_execz .Lfill0_skip2
	v_ashrrev_i32_e32 v3, 31, v2
	v_lshrrev_b32_e32 v3, 29, v3
	v_add_u32_e32 v3, v2, v3
	v_ashrrev_i32_e32 v10, 3, v3
	v_and_b32_e32 v3, -8, v3
	v_sub_u32_e32 v2, v2, v3
	v_cmp_gt_i32_e32 vcc, 0, v2
	s_nop 1
	v_cndmask_b32_e32 v3, v7, v8, vcc
	v_mul_lo_u32 v2, v2, v3
	v_add_u32_e32 v2, v2, v10
	v_mul_hi_i32 v3, v2, s22
	v_lshrrev_b32_e32 v10, 31, v3
	v_ashrrev_i32_e32 v3, 5, v3
	v_add_u32_e32 v3, v3, v10
	v_lshlrev_b32_e32 v10, 3, v3
	v_sub_u32_e32 v11, 64, v10
	v_min_i32_e32 v11, 8, v11
	v_sub_u32_e32 v12, 0, v11
	v_max_i32_e32 v11, v11, v12
	v_cvt_f32_u32_e32 v12, v11
	v_mul_lo_u32 v3, v3, s15
	v_sub_u32_e32 v2, v2, v3
	v_sub_u32_e32 v13, 0, v2
	v_rcp_iflag_f32_e32 v12, v12
	v_ashrrev_i32_e32 v3, 31, v2
	v_max_i32_e32 v2, v2, v13
	v_sub_u32_e32 v13, 0, v11
	v_mul_f32_e32 v12, 0x4f7ffffe, v12
	v_cvt_u32_f32_e32 v12, v12
	v_mul_lo_u32 v13, v13, v12
	v_mul_hi_u32 v13, v12, v13
	v_add_u32_e32 v12, v12, v13
	v_mul_hi_u32 v12, v2, v12
	v_mul_lo_u32 v12, v12, v11
	v_sub_u32_e32 v2, v2, v12
	v_sub_u32_e32 v12, v2, v11
	v_cmp_ge_u32_e32 vcc, v2, v11
	s_nop 1
	v_cndmask_b32_e32 v2, v2, v12, vcc
	v_sub_u32_e32 v12, v2, v11
	v_cmp_ge_u32_e32 vcc, v2, v11
	s_nop 1
	v_cndmask_b32_e32 v2, v2, v12, vcc
	v_xor_b32_e32 v2, v2, v3
	v_sub_u32_e32 v2, v2, v3
	v_add_u32_e32 v10, v10, v2
; #define PG8_LAS __attribute__((address_space(3)))
;     __host__ __device__ __forceinline__ bool next(int i, Unit& u) const {
;         const long L = (long)i * G + c; if (L >= nwg) return false;
;         int wgid = (int)L; { const int q = nwg / NXCD, r = nwg % NXCD, xcd = wgid % NXCD, off = wgid / NXCD; wgid = (xcd < r ? xcd * (q + 1) : r * (q + 1) + (xcd - r) * q) + off; }
;         const int nig = WGM * nN, gid = wgid / nig, fm = gid * WGM, gsz = (nM - fm) < WGM ? (nM - fm) : WGM;
;         u.pm = fm + ((wgid % nig) % gsz); u.pn = (wgid % nig) / gsz; return true;
;     }
; __device__ __forceinline__ unsigned cvt_pk_bf16(float lo, float hi) { unsigned r; asm volatile("v_cvt_pk_bf16_f32 %0, %1, %2" : "=v"(r) : "v"(lo), "v"(hi)); return r; }
; __device__ __forceinline__ float row_rstd(const float* stats, int row) { const f32x4* sp = (const f32x4*)(stats + (size_t)row * 16); const f32x4 a = sp[0], b = sp[1], c = sp[2], d = sp[3];
;     const float s = ((a[0] + a[1]) + (a[2] + a[3])) + ((b[0] + b[1]) + (b[2] + b[3])) + ((c[0] + c[1]) + (c[2] + c[3])) + ((d[0] + d[1]) + (d[2] + d[3])); return rsqrtf(s * (1.0f / 1024.0f) + 1e-6f); }
; template <class Sched> __device__ __forceinline__ void fill_rstd_table(PG8_LAS float* rsL, const float* stats, const Sched& S, int tid) {
;     Unit u; int n = 0; while (n < 8 && S.next(n, u)) ++n;
;     for (int idx = tid; idx < n * 256; idx += 512) { S.next(idx >> 8, u); rsL[idx] = row_rstd(stats, u.pm * BM + (idx & 255)); }
;     asm volatile("s_waitcnt lgkmcnt(0)" ::: "memory"); __builtin_amdgcn_s_barrier(); asm volatile("" ::: "memory");
.Lfill0_skip2:
	s_or_b64 exec, exec, s[4:5]
	v_lshl_or_b32 v2, v10, 8, v4
	v_ashrrev_i32_e32 v3, 31, v2
	v_lshlrev_b64 v[2:3], 6, v[2:3]
	v_lshl_add_u64 v[2:3], s[8:9], 0, v[2:3]
	global_load_dwordx4 v[60:63], v[2:3], off
	global_load_dwordx4 v[64:67], v[2:3], off offset:16
	global_load_dwordx4 v[68:71], v[2:3], off offset:32
	global_load_dwordx4 v[72:75], v[2:3], off offset:48
	v_add_u32_e32 v9, 0x200, v9
	v_ashrrev_i32_e32 v2, 8, v9
	v_mad_i64_i32 v[2:3], s[4:5], v2, s57, v[0:1]
	v_cmp_gt_i64_e32 vcc, s[12:13], v[2:3]
	s_and_saveexec_b64 s[4:5], vcc
	s_cbranch_execz .Lfill0_skip3
	v_ashrrev_i32_e32 v3, 31, v2
	v_lshrrev_b32_e32 v3, 29, v3
	v_add_u32_e32 v3, v2, v3
	v_ashrrev_i32_e32 v10, 3, v3
	v_and_b32_e32 v3, -8, v3
	v_sub_u32_e32 v2, v2, v3
	v_cmp_gt_i32_e32 vcc, 0, v2
	s_nop 1
	v_cndmask_b32_e32 v3, v7, v8, vcc
	v_mul_lo_u32 v2, v2, v3
	v_add_u32_e32 v2, v2, v10
	v_mul_hi_i32 v3, v2, s22
	v_lshrrev_b32_e32 v10, 31, v3
	v_ashrrev_i32_e32 v3, 5, v3
	v_add_u32_e32 v3, v3, v10
	v_lshlrev_b32_e32 v10, 3, v3
	v_sub_u32_e32 v11, 64, v10
	v_min_i32_e32 v11, 8, v11
	v_sub_u32_e32 v12, 0, v11
	v_max_i32_e32 v11, v11, v12
	v_cvt_f32_u32_e32 v12, v11
	v_mul_lo_u32 v3, v3, s15
	v_sub_u32_e32 v2, v2, v3
	v_sub_u32_e32 v13, 0, v2
	v_rcp_iflag_f32_e32 v12, v12
	v_ashrrev_i32_e32 v3, 31, v2
	v_max_i32_e32 v2, v2, v13
	v_sub_u32_e32 v13, 0, v11
	v_mul_f32_e32 v12, 0x4f7ffffe, v12
	v_cvt_u32_f32_e32 v12, v12
	v_mul_lo_u32 v13, v13, v12
	v_mul_hi_u32 v13, v12, v13
	v_add_u32_e32 v12, v12, v13
	v_mul_hi_u32 v12, v2, v12
	v_mul_lo_u32 v12, v12, v11
	v_sub_u32_e32 v2, v2, v12
	v_sub_u32_e32 v12, v2, v11
	v_cmp_ge_u32_e32 vcc, v2, v11
	s_nop 1
	v_cndmask_b32_e32 v2, v2, v12, vcc
	v_sub_u32_e32 v12, v2, v11
	v_cmp_ge_u32_e32 vcc, v2, v11
	s_nop 1
	v_cndmask_b32_e32 v2, v2, v12, vcc
	v_xor_b32_e32 v2, v2, v3
	v_sub_u32_e32 v2, v2, v3
	v_add_u32_e32 v10, v10, v2
.Lfill0_skip3:
	s_or_b64 exec, exec, s[4:5]
	v_lshl_or_b32 v2, v10, 8, v4
	v_ashrrev_i32_e32 v3, 31, v2
	v_lshlrev_b64 v[2:3], 6, v[2:3]
	v_lshl_add_u64 v[2:3], s[8:9], 0, v[2:3]
	global_load_dwordx4 v[76:79], v[2:3], off
	global_load_dwordx4 v[80:83], v[2:3], off offset:16
	global_load_dwordx4 v[84:87], v[2:3], off offset:32
	global_load_dwordx4 v[88:91], v[2:3], off offset:48
	v_add_u32_e32 v9, 0x200, v9
	s_waitcnt vmcnt(0)
	v_mov_b32_e32 v2, v29
	v_mov_b32_e32 v3, v30
	v_mov_b32_e32 v29, v31
	v_mov_b32_e32 v30, v33
	v_mov_b32_e32 v31, v34
	v_mov_b32_e32 v33, v35
	v_pk_add_f32 v[2:3], v[2:3], v[28:29]
	v_pk_add_f32 v[28:29], v[30:31], v[32:33]
	v_pk_add_f32 v[2:3], v[2:3], v[2:3] op_sel:[0,1] op_sel_hi:[1,0]
	v_pk_add_f32 v[28:29], v[28:29], v[28:29] op_sel:[0,1] op_sel_hi:[1,0]
	v_add_f32_e32 v34, v36, v37
	v_add_f32_e32 v36, v38, v39
	v_mov_b32_e32 v35, v42
	v_mov_b32_e32 v37, v43
	v_mov_b32_e32 v3, v40
	v_mov_b32_e32 v29, v41
	v_pk_add_f32 v[30:31], v[34:35], v[36:37]
	v_pk_add_f32 v[2:3], v[2:3], v[28:29]
	s_nop 0
	v_pk_add_f32 v[2:3], v[2:3], v[30:31]
	s_nop 0
	v_add_f32_e32 v2, v2, v3
	v_fmamk_f32 v2, v2, 0x3a800000, v6
	v_mul_f32_e32 v3, 0x4b800000, v2
	v_cmp_gt_f32_e32 vcc, s23, v2
	s_nop 1
	v_cndmask_b32_e32 v2, v2, v3, vcc
	v_rsq_f32_e32 v2, v2
	s_nop 0
	v_mul_f32_e32 v3, 0x45800000, v2
	v_cndmask_b32_e32 v2, v2, v3, vcc
	ds_write_b32 v5, v2
	v_add_u32_e32 v5, 0x800, v5
	v_mov_b32_e32 v2, v45
	v_mov_b32_e32 v3, v46
	v_mov_b32_e32 v45, v47
	v_mov_b32_e32 v46, v49
	v_mov_b32_e32 v47, v50
	v_mov_b32_e32 v49, v51
	v_pk_add_f32 v[2:3], v[2:3], v[44:45]
	v_pk_add_f32 v[44:45], v[46:47], v[48:49]
	v_pk_add_f32 v[2:3], v[2:3], v[2:3] op_sel:[0,1] op_sel_hi:[1,0]
	v_pk_add_f32 v[44:45], v[44:45], v[44:45] op_sel:[0,1] op_sel_hi:[1,0]
	v_add_f32_e32 v50, v52, v53
	v_add_f32_e32 v52, v54, v55
	v_mov_b32_e32 v51, v58
	v_mov_b32_e32 v53, v59
	v_mov_b32_e32 v3, v56
	v_mov_b32_e32 v45, v57
	v_pk_add_f32 v[46:47], v[50:51], v[52:53]
	v_pk_add_f32 v[2:3], v[2:3], v[44:45]
	s_nop 0
	v_pk_add_f32 v[2:3], v[2:3], v[46:47]
	s_nop 0
	v_add_f32_e32 v2, v2, v3
	v_fmamk_f32 v2, v2, 0x3a800000, v6
	v_mul_f32_e32 v3, 0x4b800000, v2
	v_cmp_gt_f32_e32 vcc, s23, v2
	s_nop 1
	v_cndmask_b32_e32 v2, v2, v3, vcc
	v_rsq_f32_e32 v2, v2
	s_nop 0
	v_mul_f32_e32 v3, 0x45800000, v2
	v_cndmask_b32_e32 v2, v2, v3, vcc
	ds_write_b32 v5, v2
	v_add_u32_e32 v5, 0x800, v5
	v_mov_b32_e32 v2, v61
	v_mov_b32_e32 v3, v62
	v_mov_b32_e32 v61, v63
	v_mov_b32_e32 v62, v65
	v_mov_b32_e32 v63, v66
	v_mov_b32_e32 v65, v67
	v_pk_add_f32 v[2:3], v[2:3], v[60:61]
	v_pk_add_f32 v[60:61], v[62:63], v[64:65]
	v_pk_add_f32 v[2:3], v[2:3], v[2:3] op_sel:[0,1] op_sel_hi:[1,0]
	v_pk_add_f32 v[60:61], v[60:61], v[60:61] op_sel:[0,1] op_sel_hi:[1,0]
	v_add_f32_e32 v66, v68, v69
	v_add_f32_e32 v68, v70, v71
	v_mov_b32_e32 v67, v74
	v_mov_b32_e32 v69, v75
	v_mov_b32_e32 v3, v72
	v_mov_b32_e32 v61, v73
	v_pk_add_f32 v[62:63], v[66:67], v[68:69]
	v_pk_add_f32 v[2:3], v[2:3], v[60:61]
	s_nop 0
	v_pk_add_f32 v[2:3], v[2:3], v[62:63]
	s_nop 0
	v_add_f32_e32 v2, v2, v3
	v_fmamk_f32 v2, v2, 0x3a800000, v6
	v_mul_f32_e32 v3, 0x4b800000, v2
	v_cmp_gt_f32_e32 vcc, s23, v2
	s_nop 1
	v_cndmask_b32_e32 v2, v2, v3, vcc
	v_rsq_f32_e32 v2, v2
	s_nop 0
	v_mul_f32_e32 v3, 0x45800000, v2
	v_cndmask_b32_e32 v2, v2, v3, vcc
	ds_write_b32 v5, v2
	v_add_u32_e32 v5, 0x800, v5
	v_mov_b32_e32 v2, v77
	v_mov_b32_e32 v3, v78
	v_mov_b32_e32 v77, v79
	v_mov_b32_e32 v78, v81
	v_mov_b32_e32 v79, v82
	v_mov_b32_e32 v81, v83
	v_pk_add_f32 v[2:3], v[2:3], v[76:77]
	v_pk_add_f32 v[76:77], v[78:79], v[80:81]
	v_pk_add_f32 v[2:3], v[2:3], v[2:3] op_sel:[0,1] op_sel_hi:[1,0]
	v_pk_add_f32 v[76:77], v[76:77], v[76:77] op_sel:[0,1] op_sel_hi:[1,0]
	v_add_f32_e32 v82, v84, v85
	v_add_f32_e32 v84, v86, v87
	v_mov_b32_e32 v83, v90
	v_mov_b32_e32 v85, v91
	v_mov_b32_e32 v3, v88
	v_mov_b32_e32 v77, v89
	v_pk_add_f32 v[78:79], v[82:83], v[84:85]
	v_pk_add_f32 v[2:3], v[2:3], v[76:77]
	s_nop 0
	v_pk_add_f32 v[2:3], v[2:3], v[78:79]
	s_nop 0
	v_add_f32_e32 v2, v2, v3
	v_fmamk_f32 v2, v2, 0x3a800000, v6
	v_mul_f32_e32 v3, 0x4b800000, v2
	v_cmp_gt_f32_e32 vcc, s23, v2
	s_nop 1
	v_cndmask_b32_e32 v2, v2, v3, vcc
	v_rsq_f32_e32 v2, v2
	s_nop 0
	v_mul_f32_e32 v3, 0x45800000, v2
	v_cndmask_b32_e32 v2, v2, v3, vcc
	ds_write_b32 v5, v2
	v_add_u32_e32 v5, 0x800, v5

; #define PG8_LAS __attribute__((address_space(3)))
;     __host__ __device__ __forceinline__ bool next(int i, Unit& u) const {
;         const long L = (long)i * G + c; if (L >= nwg) return false;
;         int wgid = (int)L; { const int q = nwg / NXCD, r = nwg % NXCD, xcd = wgid % NXCD, off = wgid / NXCD; wgid = (xcd < r ? xcd * (q + 1) : r * (q + 1) + (xcd - r) * q) + off; }
;         const int nig = WGM * nN, gid = wgid / nig, fm = gid * WGM, gsz = (nM - fm) < WGM ? (nM - fm) : WGM;
;         u.pm = fm + ((wgid % nig) % gsz); u.pn = (wgid % nig) / gsz; return true;
;     }
; __device__ __forceinline__ unsigned cvt_pk_bf16(float lo, float hi) { unsigned r; asm volatile("v_cvt_pk_bf16_f32 %0, %1, %2" : "=v"(r) : "v"(lo), "v"(hi)); return r; }
; __device__ __forceinline__ float row_rstd(const float* stats, int row) { const f32x4* sp = (const f32x4*)(stats + (size_t)row * 16); const f32x4 a = sp[0], b = sp[1], c = sp[2], d = sp[3];
;     const float s = ((a[0] + a[1]) + (a[2] + a[3])) + ((b[0] + b[1]) + (b[2] + b[3])) + ((c[0] + c[1]) + (c[2] + c[3])) + ((d[0] + d[1]) + (d[2] + d[3])); return rsqrtf(s * (1.0f / 1024.0f) + 1e-6f); }
; template <class Sched> __device__ __forceinline__ void fill_rstd_table(PG8_LAS float* rsL, const float* stats, const Sched& S, int tid) {
;     Unit u; int n = 0; while (n < 8 && S.next(n, u)) ++n;
;     for (int idx = tid; idx < n * 256; idx += 512) { S.next(idx >> 8, u); rsL[idx] = row_rstd(stats, u.pm * BM + (idx & 255)); }
;     asm volatile("s_waitcnt lgkmcnt(0)" ::: "memory"); __builtin_amdgcn_s_barrier(); asm volatile("" ::: "memory");
.LBB0_388:
	s_waitcnt lgkmcnt(0)
	s_add_u32 s6, s6, s38
	s_addc_u32 s7, s7, 0
	v_cmp_gt_i32_e32 vcc, s16, v128
	s_and_saveexec_b64 s[8:9], vcc
	s_cbranch_execz .LBB0_393
	s_add_u32 s10, s6, 0x400000
	v_lshl_add_u32 v0, v128, 2, 0
	s_addc_u32 s11, s7, 0
	v_and_b32_e32 v4, 0xff, v128
	v_add_u32_e32 v5, 0x22000, v0
	s_mov_b64 s[12:13], 0
	v_mov_b32_e32 v10, s14
	v_mov_b64_e32 v[0:1], s[48:49]
	s_mov_b64 s[14:15], 0x300
	s_movk_i32 s17, 0x60
	s_mov_b32 s18, 0x2aaaaaab
	v_mov_b32_e32 v6, 0x358637bd
	s_mov_b32 s19, 0x800000
	v_mov_b32_e32 v7, 0x60
	v_mov_b32_e32 v8, 0x61
	v_mov_b32_e32 v9, v128
	v_ashrrev_i32_e32 v2, 8, v9
	v_mad_i64_i32 v[2:3], s[4:5], v2, s56, v[0:1]
	v_cmp_gt_i64_e32 vcc, s[14:15], v[2:3]
	s_and_saveexec_b64 s[4:5], vcc
	s_cbranch_execz .Lfill1_skip0
	v_ashrrev_i32_e32 v3, 31, v2
	v_lshrrev_b32_e32 v3, 29, v3
	v_add_u32_e32 v3, v2, v3
	v_ashrrev_i32_e32 v10, 3, v3
	v_and_b32_e32 v3, -8, v3
	v_sub_u32_e32 v2, v2, v3
	v_cmp_gt_i32_e32 vcc, 0, v2
	s_nop 1
	v_cndmask_b32_e32 v3, v7, v8, vcc
	v_mul_lo_u32 v2, v2, v3
	v_add_u32_e32 v2, v2, v10
	v_mul_hi_i32 v3, v2, s18
	v_lshrrev_b32_e32 v10, 31, v3
	v_ashrrev_i32_e32 v3, 4, v3
	v_add_u32_e32 v3, v3, v10
	v_lshlrev_b32_e32 v10, 3, v3
	v_sub_u32_e32 v11, 64, v10
	v_min_i32_e32 v11, 8, v11
	v_sub_u32_e32 v12, 0, v11
	v_max_i32_e32 v11, v11, v12
	v_cvt_f32_u32_e32 v12, v11
	v_mul_lo_u32 v3, v3, s17
	v_sub_u32_e32 v2, v2, v3
	v_sub_u32_e32 v13, 0, v2
	v_rcp_iflag_f32_e32 v12, v12
	v_ashrrev_i32_e32 v3, 31, v2
	v_max_i32_e32 v2, v2, v13
	v_sub_u32_e32 v13, 0, v11
	v_mul_f32_e32 v12, 0x4f7ffffe, v12
	v_cvt_u32_f32_e32 v12, v12
	v_mul_lo_u32 v13, v13, v12
	v_mul_hi_u32 v13, v12, v13
	v_add_u32_e32 v12, v12, v13
	v_mul_hi_u32 v12, v2, v12
	v_mul_lo_u32 v12, v12, v11
	v_sub_u32_e32 v2, v2, v12
	v_sub_u32_e32 v12, v2, v11
	v_cmp_ge_u32_e32 vcc, v2, v11
	s_nop 1
	v_cndmask_b32_e32 v2, v2, v12, vcc
	v_sub_u32_e32 v12, v2, v11
	v_cmp_ge_u32_e32 vcc, v2, v11
	s_nop 1
	v_cndmask_b32_e32 v2, v2, v12, vcc
	v_xor_b32_e32 v2, v2, v3
	v_sub_u32_e32 v2, v2, v3
	v_add_u32_e32 v10, v10, v2
.Lfill1_skip0:
	s_or_b64 exec, exec, s[4:5]
	v_lshl_or_b32 v2, v10, 8, v4
	v_ashrrev_i32_e32 v3, 31, v2
	v_lshlrev_b64 v[2:3], 6, v[2:3]
	v_lshl_add_u64 v[2:3], s[10:11], 0, v[2:3]
	global_load_dwordx4 v[28:31], v[2:3], off
	global_load_dwordx4 v[32:35], v[2:3], off offset:16
	global_load_dwordx4 v[36:39], v[2:3], off offset:32
	global_load_dwordx4 v[40:43], v[2:3], off offset:48
	v_add_u32_e32 v9, 0x200, v9
	v_ashrrev_i32_e32 v2, 8, v9
	v_mad_i64_i32 v[2:3], s[4:5], v2, s56, v[0:1]
	v_cmp_gt_i64_e32 vcc, s[14:15], v[2:3]
	s_and_saveexec_b64 s[4:5], vcc
	s_cbranch_execz .Lfill1_skip1
	v_ashrrev_i32_e32 v3, 31, v2
	v_lshrrev_b32_e32 v3, 29, v3
	v_add_u32_e32 v3, v2, v3
	v_ashrrev_i32_e32 v10, 3, v3
	v_and_b32_e32 v3, -8, v3
	v_sub_u32_e32 v2, v2, v3
	v_cmp_gt_i32_e32 vcc, 0, v2
	s_nop 1
	v_cndmask_b32_e32 v3, v7, v8, vcc
	v_mul_lo_u32 v2, v2, v3
	v_add_u32_e32 v2, v2, v10
	v_mul_hi_i32 v3, v2, s18
	v_lshrrev_b32_e32 v10, 31, v3
	v_ashrrev_i32_e32 v3, 4, v3
	v_add_u32_e32 v3, v3, v10
	v_lshlrev_b32_e32 v10, 3, v3
	v_sub_u32_e32 v11, 64, v10
	v_min_i32_e32 v11, 8, v11
	v_sub_u32_e32 v12, 0, v11
	v_max_i32_e32 v11, v11, v12
	v_cvt_f32_u32_e32 v12, v11
	v_mul_lo_u32 v3, v3, s17
	v_sub_u32_e32 v2, v2, v3
	v_sub_u32_e32 v13, 0, v2
	v_rcp_iflag_f32_e32 v12, v12
	v_ashrrev_i32_e32 v3, 31, v2
	v_max_i32_e32 v2, v2, v13
	v_sub_u32_e32 v13, 0, v11
	v_mul_f32_e32 v12, 0x4f7ffffe, v12
	v_cvt_u32_f32_e32 v12, v12
	v_mul_lo_u32 v13, v13, v12
	v_mul_hi_u32 v13, v12, v13
	v_add_u32_e32 v12, v12, v13
	v_mul_hi_u32 v12, v2, v12
	v_mul_lo_u32 v12, v12, v11
	v_sub_u32_e32 v2, v2, v12
	v_sub_u32_e32 v12, v2, v11
	v_cmp_ge_u32_e32 vcc, v2, v11
	s_nop 1
	v_cndmask_b32_e32 v2, v2, v12, vcc
	v_sub_u32_e32 v12, v2, v11
	v_cmp_ge_u32_e32 vcc, v2, v11
	s_nop 1
	v_cndmask_b32_e32 v2, v2, v12, vcc
	v_xor_b32_e32 v2, v2, v3
	v_sub_u32_e32 v2, v2, v3
	v_add_u32_e32 v10, v10, v2
.Lfill1_skip1:
	s_or_b64 exec, exec, s[4:5]
	v_lshl_or_b32 v2, v10, 8, v4
	v_ashrrev_i32_e32 v3, 31, v2
	v_lshlrev_b64 v[2:3], 6, v[2:3]
	v_lshl_add_u64 v[2:3], s[10:11], 0, v[2:3]
	global_load_dwordx4 v[44:47], v[2:3], off
	global_load_dwordx4 v[48:51], v[2:3], off offset:16
	global_load_dwordx4 v[52:55], v[2:3], off offset:32
	global_load_dwordx4 v[56:59], v[2:3], off offset:48
	v_add_u32_e32 v9, 0x200, v9
	v_ashrrev_i32_e32 v2, 8, v9
	v_mad_i64_i32 v[2:3], s[4:5], v2, s56, v[0:1]
	v_cmp_gt_i64_e32 vcc, s[14:15], v[2:3]
	s_and_saveexec_b64 s[4:5], vcc
	s_cbranch_execz .Lfill1_skip2
	v_ashrrev_i32_e32 v3, 31, v2
	v_lshrrev_b32_e32 v3, 29, v3
	v_add_u32_e32 v3, v2, v3
	v_ashrrev_i32_e32 v10, 3, v3
	v_and_b32_e32 v3, -8, v3
	v_sub_u32_e32 v2, v2, v3
	v_cmp_gt_i32_e32 vcc, 0, v2
	s_nop 1
	v_cndmask_b32_e32 v3, v7, v8, vcc
	v_mul_lo_u32 v2, v2, v3
	v_add_u32_e32 v2, v2, v10
	v_mul_hi_i32 v3, v2, s18
	v_lshrrev_b32_e32 v10, 31, v3
	v_ashrrev_i32_e32 v3, 4, v3
	v_add_u32_e32 v3, v3, v10
	v_lshlrev_b32_e32 v10, 3, v3
	v_sub_u32_e32 v11, 64, v10
	v_min_i32_e32 v11, 8, v11
	v_sub_u32_e32 v12, 0, v11
	v_max_i32_e32 v11, v11, v12
	v_cvt_f32_u32_e32 v12, v11
	v_mul_lo_u32 v3, v3, s17
	v_sub_u32_e32 v2, v2, v3
	v_sub_u32_e32 v13, 0, v2
	v_rcp_iflag_f32_e32 v12, v12
	v_ashrrev_i32_e32 v3, 31, v2
	v_max_i32_e32 v2, v2, v13
	v_sub_u32_e32 v13, 0, v11
	v_mul_f32_e32 v12, 0x4f7ffffe, v12
	v_cvt_u32_f32_e32 v12, v12
	v_mul_lo_u32 v13, v13, v12
	v_mul_hi_u32 v13, v12, v13
	v_add_u32_e32 v12, v12, v13
	v_mul_hi_u32 v12, v2, v12
	v_mul_lo_u32 v12, v12, v11
	v_sub_u32_e32 v2, v2, v12
	v_sub_u32_e32 v12, v2, v11
	v_cmp_ge_u32_e32 vcc, v2, v11
	s_nop 1
	v_cndmask_b32_e32 v2, v2, v12, vcc
	v_sub_u32_e32 v12, v2, v11
	v_cmp_ge_u32_e32 vcc, v2, v11
	s_nop 1
	v_cndmask_b32_e32 v2, v2, v12, vcc
	v_xor_b32_e32 v2, v2, v3
	v_sub_u32_e32 v2, v2, v3
	v_add_u32_e32 v10, v10, v2
; #define PG8_LAS __attribute__((address_space(3)))
;     __host__ __device__ __forceinline__ bool next(int i, Unit& u) const {
;         const long L = (long)i * G + c; if (L >= nwg) return false;
;         int wgid = (int)L; { const int q = nwg / NXCD, r = nwg % NXCD, xcd = wgid % NXCD, off = wgid / NXCD; wgid = (xcd < r ? xcd * (q + 1) : r * (q + 1) + (xcd - r) * q) + off; }
;         const int nig = WGM * nN, gid = wgid / nig, fm = gid * WGM, gsz = (nM - fm) < WGM ? (nM - fm) : WGM;
;         u.pm = fm + ((wgid % nig) % gsz); u.pn = (wgid % nig) / gsz; return true;
;     }
; __device__ __forceinline__ unsigned cvt_pk_bf16(float lo, float hi) { unsigned r; asm volatile("v_cvt_pk_bf16_f32 %0, %1, %2" : "=v"(r) : "v"(lo), "v"(hi)); return r; }
; __device__ __forceinline__ float row_rstd(const float* stats, int row) { const f32x4* sp = (const f32x4*)(stats + (size_t)row * 16); const f32x4 a = sp[0], b = sp[1], c = sp[2], d = sp[3];
;     const float s = ((a[0] + a[1]) + (a[2] + a[3])) + ((b[0] + b[1]) + (b[2] + b[3])) + ((c[0] + c[1]) + (c[2] + c[3])) + ((d[0] + d[1]) + (d[2] + d[3])); return rsqrtf(s * (1.0f / 1024.0f) + 1e-6f); }
; template <class Sched> __device__ __forceinline__ void fill_rstd_table(PG8_LAS float* rsL, const float* stats, const Sched& S, int tid) {
;     Unit u; int n = 0; while (n < 8 && S.next(n, u)) ++n;
;     for (int idx = tid; idx < n * 256; idx += 512) { S.next(idx >> 8, u); rsL[idx] = row_rstd(stats, u.pm * BM + (idx & 255)); }
;     asm volatile("s_waitcnt lgkmcnt(0)" ::: "memory"); __builtin_amdgcn_s_barrier(); asm volatile("" ::: "memory");
.Lfill1_skip2:
	s_or_b64 exec, exec, s[4:5]
	v_lshl_or_b32 v2, v10, 8, v4
	v_ashrrev_i32_e32 v3, 31, v2
	v_lshlrev_b64 v[2:3], 6, v[2:3]
	v_lshl_add_u64 v[2:3], s[10:11], 0, v[2:3]
	global_load_dwordx4 v[60:63], v[2:3], off
	global_load_dwordx4 v[64:67], v[2:3], off offset:16
	global_load_dwordx4 v[68:71], v[2:3], off offset:32
	global_load_dwordx4 v[72:75], v[2:3], off offset:48
	v_add_u32_e32 v9, 0x200, v9
	v_ashrrev_i32_e32 v2, 8, v9
	v_mad_i64_i32 v[2:3], s[4:5], v2, s56, v[0:1]
	v_cmp_gt_i64_e32 vcc, s[14:15], v[2:3]
	s_and_saveexec_b64 s[4:5], vcc
	s_cbranch_execz .Lfill1_skip3
	v_ashrrev_i32_e32 v3, 31, v2
	v_lshrrev_b32_e32 v3, 29, v3
	v_add_u32_e32 v3, v2, v3
	v_ashrrev_i32_e32 v10, 3, v3
	v_and_b32_e32 v3, -8, v3
	v_sub_u32_e32 v2, v2, v3
	v_cmp_gt_i32_e32 vcc, 0, v2
	s_nop 1
	v_cndmask_b32_e32 v3, v7, v8, vcc
	v_mul_lo_u32 v2, v2, v3
	v_add_u32_e32 v2, v2, v10
	v_mul_hi_i32 v3, v2, s18
	v_lshrrev_b32_e32 v10, 31, v3
	v_ashrrev_i32_e32 v3, 4, v3
	v_add_u32_e32 v3, v3, v10
	v_lshlrev_b32_e32 v10, 3, v3
	v_sub_u32_e32 v11, 64, v10
	v_min_i32_e32 v11, 8, v11
	v_sub_u32_e32 v12, 0, v11
	v_max_i32_e32 v11, v11, v12
	v_cvt_f32_u32_e32 v12, v11
	v_mul_lo_u32 v3, v3, s17
	v_sub_u32_e32 v2, v2, v3
	v_sub_u32_e32 v13, 0, v2
	v_rcp_iflag_f32_e32 v12, v12
	v_ashrrev_i32_e32 v3, 31, v2
	v_max_i32_e32 v2, v2, v13
	v_sub_u32_e32 v13, 0, v11
	v_mul_f32_e32 v12, 0x4f7ffffe, v12
	v_cvt_u32_f32_e32 v12, v12
	v_mul_lo_u32 v13, v13, v12
	v_mul_hi_u32 v13, v12, v13
	v_add_u32_e32 v12, v12, v13
	v_mul_hi_u32 v12, v2, v12
	v_mul_lo_u32 v12, v12, v11
	v_sub_u32_e32 v2, v2, v12
	v_sub_u32_e32 v12, v2, v11
	v_cmp_ge_u32_e32 vcc, v2, v11
	s_nop 1
	v_cndmask_b32_e32 v2, v2, v12, vcc
	v_sub_u32_e32 v12, v2, v11
	v_cmp_ge_u32_e32 vcc, v2, v11
	s_nop 1
	v_cndmask_b32_e32 v2, v2, v12, vcc
	v_xor_b32_e32 v2, v2, v3
	v_sub_u32_e32 v2, v2, v3
	v_add_u32_e32 v10, v10, v2
.Lfill1_skip3:
	s_or_b64 exec, exec, s[4:5]
	v_lshl_or_b32 v2, v10, 8, v4
	v_ashrrev_i32_e32 v3, 31, v2
	v_lshlrev_b64 v[2:3], 6, v[2:3]
	v_lshl_add_u64 v[2:3], s[10:11], 0, v[2:3]
	global_load_dwordx4 v[76:79], v[2:3], off
	global_load_dwordx4 v[80:83], v[2:3], off offset:16
	global_load_dwordx4 v[84:87], v[2:3], off offset:32
	global_load_dwordx4 v[88:91], v[2:3], off offset:48
	v_add_u32_e32 v9, 0x200, v9
	s_waitcnt vmcnt(0)
	v_mov_b32_e32 v2, v29
	v_mov_b32_e32 v3, v30
	v_mov_b32_e32 v29, v31
	v_mov_b32_e32 v30, v33
	v_mov_b32_e32 v31, v34
	v_mov_b32_e32 v33, v35
	v_pk_add_f32 v[2:3], v[2:3], v[28:29]
	v_pk_add_f32 v[28:29], v[30:31], v[32:33]
	v_pk_add_f32 v[2:3], v[2:3], v[2:3] op_sel:[0,1] op_sel_hi:[1,0]
	v_pk_add_f32 v[28:29], v[28:29], v[28:29] op_sel:[0,1] op_sel_hi:[1,0]
	v_add_f32_e32 v34, v36, v37
	v_add_f32_e32 v36, v38, v39
	v_mov_b32_e32 v35, v42
	v_mov_b32_e32 v37, v43
	v_mov_b32_e32 v3, v40
	v_mov_b32_e32 v29, v41
	v_pk_add_f32 v[30:31], v[34:35], v[36:37]
	v_pk_add_f32 v[2:3], v[2:3], v[28:29]
	s_nop 0
	v_pk_add_f32 v[2:3], v[2:3], v[30:31]
	s_nop 0
	v_add_f32_e32 v2, v2, v3
	v_fmamk_f32 v2, v2, 0x3a800000, v6
	v_mul_f32_e32 v3, 0x4b800000, v2
	v_cmp_gt_f32_e32 vcc, s19, v2
	s_nop 1
	v_cndmask_b32_e32 v2, v2, v3, vcc
	v_rsq_f32_e32 v2, v2
	s_nop 0
	v_mul_f32_e32 v3, 0x45800000, v2
	v_cndmask_b32_e32 v2, v2, v3, vcc
	ds_write_b32 v5, v2
	v_add_u32_e32 v5, 0x800, v5
	v_mov_b32_e32 v2, v45
	v_mov_b32_e32 v3, v46
	v_mov_b32_e32 v45, v47
	v_mov_b32_e32 v46, v49
	v_mov_b32_e32 v47, v50
	v_mov_b32_e32 v49, v51
	v_pk_add_f32 v[2:3], v[2:3], v[44:45]
	v_pk_add_f32 v[44:45], v[46:47], v[48:49]
	v_pk_add_f32 v[2:3], v[2:3], v[2:3] op_sel:[0,1] op_sel_hi:[1,0]
	v_pk_add_f32 v[44:45], v[44:45], v[44:45] op_sel:[0,1] op_sel_hi:[1,0]
	v_add_f32_e32 v50, v52, v53
	v_add_f32_e32 v52, v54, v55
	v_mov_b32_e32 v51, v58
	v_mov_b32_e32 v53, v59
	v_mov_b32_e32 v3, v56
	v_mov_b32_e32 v45, v57
	v_pk_add_f32 v[46:47], v[50:51], v[52:53]
	v_pk_add_f32 v[2:3], v[2:3], v[44:45]
	s_nop 0
	v_pk_add_f32 v[2:3], v[2:3], v[46:47]
	s_nop 0
	v_add_f32_e32 v2, v2, v3
	v_fmamk_f32 v2, v2, 0x3a800000, v6
	v_mul_f32_e32 v3, 0x4b800000, v2
	v_cmp_gt_f32_e32 vcc, s19, v2
	s_nop 1
	v_cndmask_b32_e32 v2, v2, v3, vcc
	v_rsq_f32_e32 v2, v2
	s_nop 0
	v_mul_f32_e32 v3, 0x45800000, v2
	v_cndmask_b32_e32 v2, v2, v3, vcc
	ds_write_b32 v5, v2
	v_add_u32_e32 v5, 0x800, v5
	v_mov_b32_e32 v2, v61
	v_mov_b32_e32 v3, v62
	v_mov_b32_e32 v61, v63
	v_mov_b32_e32 v62, v65
	v_mov_b32_e32 v63, v66
	v_mov_b32_e32 v65, v67
	v_pk_add_f32 v[2:3], v[2:3], v[60:61]
	v_pk_add_f32 v[60:61], v[62:63], v[64:65]
	v_pk_add_f32 v[2:3], v[2:3], v[2:3] op_sel:[0,1] op_sel_hi:[1,0]
	v_pk_add_f32 v[60:61], v[60:61], v[60:61] op_sel:[0,1] op_sel_hi:[1,0]
	v_add_f32_e32 v66, v68, v69
	v_add_f32_e32 v68, v70, v71
	v_mov_b32_e32 v67, v74
	v_mov_b32_e32 v69, v75
	v_mov_b32_e32 v3, v72
	v_mov_b32_e32 v61, v73
	v_pk_add_f32 v[62:63], v[66:67], v[68:69]
	v_pk_add_f32 v[2:3], v[2:3], v[60:61]
	s_nop 0
	v_pk_add_f32 v[2:3], v[2:3], v[62:63]
	s_nop 0
	v_add_f32_e32 v2, v2, v3
	v_fmamk_f32 v2, v2, 0x3a800000, v6
	v_mul_f32_e32 v3, 0x4b800000, v2
	v_cmp_gt_f32_e32 vcc, s19, v2
	s_nop 1
	v_cndmask_b32_e32 v2, v2, v3, vcc
	v_rsq_f32_e32 v2, v2
	s_nop 0
	v_mul_f32_e32 v3, 0x45800000, v2
	v_cndmask_b32_e32 v2, v2, v3, vcc
	ds_write_b32 v5, v2
	v_add_u32_e32 v5, 0x800, v5
	v_mov_b32_e32 v2, v77
	v_mov_b32_e32 v3, v78
	v_mov_b32_e32 v77, v79
	v_mov_b32_e32 v78, v81
	v_mov_b32_e32 v79, v82
	v_mov_b32_e32 v81, v83
	v_pk_add_f32 v[2:3], v[2:3], v[76:77]
	v_pk_add_f32 v[76:77], v[78:79], v[80:81]
	v_pk_add_f32 v[2:3], v[2:3], v[2:3] op_sel:[0,1] op_sel_hi:[1,0]
	v_pk_add_f32 v[76:77], v[76:77], v[76:77] op_sel:[0,1] op_sel_hi:[1,0]
	v_add_f32_e32 v82, v84, v85
	v_add_f32_e32 v84, v86, v87
	v_mov_b32_e32 v83, v90
	v_mov_b32_e32 v85, v91
	v_mov_b32_e32 v3, v88
	v_mov_b32_e32 v77, v89
	v_pk_add_f32 v[78:79], v[82:83], v[84:85]
	v_pk_add_f32 v[2:3], v[2:3], v[76:77]
	s_nop 0
	v_pk_add_f32 v[2:3], v[2:3], v[78:79]
	s_nop 0
	v_add_f32_e32 v2, v2, v3
	v_fmamk_f32 v2, v2, 0x3a800000, v6
	v_mul_f32_e32 v3, 0x4b800000, v2
	v_cmp_gt_f32_e32 vcc, s19, v2
	s_nop 1
	v_cndmask_b32_e32 v2, v2, v3, vcc
	v_rsq_f32_e32 v2, v2
	s_nop 0
	v_mul_f32_e32 v3, 0x45800000, v2
	v_cndmask_b32_e32 v2, v2, v3, vcc
	ds_write_b32 v5, v2
	v_add_u32_e32 v5, 0x800, v5

; #define PG8_LAS __attribute__((address_space(3)))
;     __host__ __device__ __forceinline__ bool next(int i, Unit& u) const {
;         const long L = (long)i * G + c; if (L >= nwg) return false;
;         int wgid = (int)L; { const int q = nwg / NXCD, r = nwg % NXCD, xcd = wgid % NXCD, off = wgid / NXCD; wgid = (xcd < r ? xcd * (q + 1) : r * (q + 1) + (xcd - r) * q) + off; }
;         const int nig = WGM * nN, gid = wgid / nig, fm = gid * WGM, gsz = (nM - fm) < WGM ? (nM - fm) : WGM;
;         u.pm = fm + ((wgid % nig) % gsz); u.pn = (wgid % nig) / gsz; return true;
;     }
; __device__ __forceinline__ unsigned cvt_pk_bf16(float lo, float hi) { unsigned r; asm volatile("v_cvt_pk_bf16_f32 %0, %1, %2" : "=v"(r) : "v"(lo), "v"(hi)); return r; }
; __device__ __forceinline__ float row_rstd(const float* stats, int row) { const f32x4* sp = (const f32x4*)(stats + (size_t)row * 16); const f32x4 a = sp[0], b = sp[1], c = sp[2], d = sp[3];
;     const float s = ((a[0] + a[1]) + (a[2] + a[3])) + ((b[0] + b[1]) + (b[2] + b[3])) + ((c[0] + c[1]) + (c[2] + c[3])) + ((d[0] + d[1]) + (d[2] + d[3])); return rsqrtf(s * (1.0f / 1024.0f) + 1e-6f); }
; template <class Sched> __device__ __forceinline__ void fill_rstd_table(PG8_LAS float* rsL, const float* stats, const Sched& S, int tid) {
;     Unit u; int n = 0; while (n < 8 && S.next(n, u)) ++n;
;     for (int idx = tid; idx < n * 256; idx += 512) { S.next(idx >> 8, u); rsL[idx] = row_rstd(stats, u.pm * BM + (idx & 255)); }
;     asm volatile("s_waitcnt lgkmcnt(0)" ::: "memory"); __builtin_amdgcn_s_barrier(); asm volatile("" ::: "memory");
.LBB0_977:
	s_waitcnt lgkmcnt(0)
	s_add_u32 s10, s10, s14
	s_addc_u32 s11, s11, 0
	v_cmp_gt_i32_e32 vcc, s20, v154
	s_and_saveexec_b64 s[12:13], vcc
	s_cbranch_execz .LBB0_982
	s_add_u32 s14, s10, 0x400000
	v_lshl_add_u32 v0, v154, 2, 0
	s_addc_u32 s15, s11, 0
	v_and_b32_e32 v4, 0xff, v154
	v_add_u32_e32 v5, 0x22000, v0
	s_mov_b64 s[16:17], 0
	v_mov_b32_e32 v10, s18
	v_mov_b64_e32 v[0:1], s[6:7]
	s_mov_b64 s[18:19], 0x580
	s_movk_i32 s21, 0xb0
	s_mov_b32 s22, 0x2e8ba2e9
	v_mov_b32_e32 v6, 0x358637bd
	s_mov_b32 s23, 0x800000
	v_mov_b32_e32 v7, 0xb0
	v_mov_b32_e32 v8, 0xb1
	v_mov_b32_e32 v9, v154
	v_ashrrev_i32_e32 v2, 8, v9
	v_mad_i64_i32 v[2:3], s[4:5], v2, s39, v[0:1]
	v_cmp_gt_i64_e32 vcc, s[18:19], v[2:3]
	s_and_saveexec_b64 s[4:5], vcc
	s_cbranch_execz .Lfill2_skip0
	v_ashrrev_i32_e32 v3, 31, v2
	v_lshrrev_b32_e32 v3, 29, v3
	v_add_u32_e32 v3, v2, v3
	v_ashrrev_i32_e32 v10, 3, v3
	v_and_b32_e32 v3, -8, v3
	v_sub_u32_e32 v2, v2, v3
	v_cmp_gt_i32_e32 vcc, 0, v2
	s_nop 1
	v_cndmask_b32_e32 v3, v7, v8, vcc
	v_mul_lo_u32 v2, v2, v3
	v_add_u32_e32 v2, v2, v10
	v_mul_hi_i32 v3, v2, s22
	v_lshrrev_b32_e32 v10, 31, v3
	v_ashrrev_i32_e32 v3, 5, v3
	v_add_u32_e32 v3, v3, v10
	v_lshlrev_b32_e32 v10, 3, v3
	v_sub_u32_e32 v11, 64, v10
	v_min_i32_e32 v11, 8, v11
	v_sub_u32_e32 v12, 0, v11
	v_max_i32_e32 v11, v11, v12
	v_cvt_f32_u32_e32 v12, v11
	v_mul_lo_u32 v3, v3, s21
	v_sub_u32_e32 v2, v2, v3
	v_sub_u32_e32 v13, 0, v2
	v_rcp_iflag_f32_e32 v12, v12
	v_ashrrev_i32_e32 v3, 31, v2
	v_max_i32_e32 v2, v2, v13
	v_sub_u32_e32 v13, 0, v11
	v_mul_f32_e32 v12, 0x4f7ffffe, v12
	v_cvt_u32_f32_e32 v12, v12
	v_mul_lo_u32 v13, v13, v12
	v_mul_hi_u32 v13, v12, v13
	v_add_u32_e32 v12, v12, v13
	v_mul_hi_u32 v12, v2, v12
	v_mul_lo_u32 v12, v12, v11
	v_sub_u32_e32 v2, v2, v12
	v_sub_u32_e32 v12, v2, v11
	v_cmp_ge_u32_e32 vcc, v2, v11
	s_nop 1
	v_cndmask_b32_e32 v2, v2, v12, vcc
	v_sub_u32_e32 v12, v2, v11
	v_cmp_ge_u32_e32 vcc, v2, v11
	s_nop 1
	v_cndmask_b32_e32 v2, v2, v12, vcc
	v_xor_b32_e32 v2, v2, v3
	v_sub_u32_e32 v2, v2, v3
	v_add_u32_e32 v10, v10, v2
.Lfill2_skip0:
	s_or_b64 exec, exec, s[4:5]
	v_lshl_or_b32 v2, v10, 8, v4
	v_ashrrev_i32_e32 v3, 31, v2
	v_lshlrev_b64 v[2:3], 6, v[2:3]
	v_lshl_add_u64 v[2:3], s[14:15], 0, v[2:3]
	global_load_dwordx4 v[28:31], v[2:3], off
	global_load_dwordx4 v[32:35], v[2:3], off offset:16
	global_load_dwordx4 v[36:39], v[2:3], off offset:32
	global_load_dwordx4 v[40:43], v[2:3], off offset:48
	v_add_u32_e32 v9, 0x200, v9
	v_ashrrev_i32_e32 v2, 8, v9
	v_mad_i64_i32 v[2:3], s[4:5], v2, s39, v[0:1]
	v_cmp_gt_i64_e32 vcc, s[18:19], v[2:3]
	s_and_saveexec_b64 s[4:5], vcc
	s_cbranch_execz .Lfill2_skip1
	v_ashrrev_i32_e32 v3, 31, v2
	v_lshrrev_b32_e32 v3, 29, v3
	v_add_u32_e32 v3, v2, v3
	v_ashrrev_i32_e32 v10, 3, v3
	v_and_b32_e32 v3, -8, v3
	v_sub_u32_e32 v2, v2, v3
	v_cmp_gt_i32_e32 vcc, 0, v2
	s_nop 1
	v_cndmask_b32_e32 v3, v7, v8, vcc
	v_mul_lo_u32 v2, v2, v3
	v_add_u32_e32 v2, v2, v10
	v_mul_hi_i32 v3, v2, s22
	v_lshrrev_b32_e32 v10, 31, v3
	v_ashrrev_i32_e32 v3, 5, v3
	v_add_u32_e32 v3, v3, v10
	v_lshlrev_b32_e32 v10, 3, v3
	v_sub_u32_e32 v11, 64, v10
	v_min_i32_e32 v11, 8, v11
	v_sub_u32_e32 v12, 0, v11
	v_max_i32_e32 v11, v11, v12
	v_cvt_f32_u32_e32 v12, v11
	v_mul_lo_u32 v3, v3, s21
	v_sub_u32_e32 v2, v2, v3
	v_sub_u32_e32 v13, 0, v2
	v_rcp_iflag_f32_e32 v12, v12
	v_ashrrev_i32_e32 v3, 31, v2
	v_max_i32_e32 v2, v2, v13
	v_sub_u32_e32 v13, 0, v11
	v_mul_f32_e32 v12, 0x4f7ffffe, v12
	v_cvt_u32_f32_e32 v12, v12
	v_mul_lo_u32 v13, v13, v12
	v_mul_hi_u32 v13, v12, v13
	v_add_u32_e32 v12, v12, v13
	v_mul_hi_u32 v12, v2, v12
	v_mul_lo_u32 v12, v12, v11
	v_sub_u32_e32 v2, v2, v12
	v_sub_u32_e32 v12, v2, v11
	v_cmp_ge_u32_e32 vcc, v2, v11
	s_nop 1
	v_cndmask_b32_e32 v2, v2, v12, vcc
	v_sub_u32_e32 v12, v2, v11
	v_cmp_ge_u32_e32 vcc, v2, v11
	s_nop 1
	v_cndmask_b32_e32 v2, v2, v12, vcc
	v_xor_b32_e32 v2, v2, v3
	v_sub_u32_e32 v2, v2, v3
	v_add_u32_e32 v10, v10, v2
.Lfill2_skip1:
	s_or_b64 exec, exec, s[4:5]
	v_lshl_or_b32 v2, v10, 8, v4
	v_ashrrev_i32_e32 v3, 31, v2
	v_lshlrev_b64 v[2:3], 6, v[2:3]
	v_lshl_add_u64 v[2:3], s[14:15], 0, v[2:3]
	global_load_dwordx4 v[44:47], v[2:3], off
	global_load_dwordx4 v[48:51], v[2:3], off offset:16
	global_load_dwordx4 v[52:55], v[2:3], off offset:32
	global_load_dwordx4 v[56:59], v[2:3], off offset:48
	v_add_u32_e32 v9, 0x200, v9
	v_ashrrev_i32_e32 v2, 8, v9
	v_mad_i64_i32 v[2:3], s[4:5], v2, s39, v[0:1]
	v_cmp_gt_i64_e32 vcc, s[18:19], v[2:3]
	s_and_saveexec_b64 s[4:5], vcc
	s_cbranch_execz .Lfill2_skip2
	v_ashrrev_i32_e32 v3, 31, v2
	v_lshrrev_b32_e32 v3, 29, v3
	v_add_u32_e32 v3, v2, v3
	v_ashrrev_i32_e32 v10, 3, v3
	v_and_b32_e32 v3, -8, v3
	v_sub_u32_e32 v2, v2, v3
	v_cmp_gt_i32_e32 vcc, 0, v2
	s_nop 1
	v_cndmask_b32_e32 v3, v7, v8, vcc
	v_mul_lo_u32 v2, v2, v3
	v_add_u32_e32 v2, v2, v10
	v_mul_hi_i32 v3, v2, s22
	v_lshrrev_b32_e32 v10, 31, v3
	v_ashrrev_i32_e32 v3, 5, v3
	v_add_u32_e32 v3, v3, v10
	v_lshlrev_b32_e32 v10, 3, v3
	v_sub_u32_e32 v11, 64, v10
	v_min_i32_e32 v11, 8, v11
	v_sub_u32_e32 v12, 0, v11
	v_max_i32_e32 v11, v11, v12
	v_cvt_f32_u32_e32 v12, v11
	v_mul_lo_u32 v3, v3, s21
	v_sub_u32_e32 v2, v2, v3
	v_sub_u32_e32 v13, 0, v2
	v_rcp_iflag_f32_e32 v12, v12
	v_ashrrev_i32_e32 v3, 31, v2
	v_max_i32_e32 v2, v2, v13
	v_sub_u32_e32 v13, 0, v11
	v_mul_f32_e32 v12, 0x4f7ffffe, v12
	v_cvt_u32_f32_e32 v12, v12
	v_mul_lo_u32 v13, v13, v12
	v_mul_hi_u32 v13, v12, v13
	v_add_u32_e32 v12, v12, v13
	v_mul_hi_u32 v12, v2, v12
	v_mul_lo_u32 v12, v12, v11
	v_sub_u32_e32 v2, v2, v12
	v_sub_u32_e32 v12, v2, v11
	v_cmp_ge_u32_e32 vcc, v2, v11
	s_nop 1
	v_cndmask_b32_e32 v2, v2, v12, vcc
	v_sub_u32_e32 v12, v2, v11
	v_cmp_ge_u32_e32 vcc, v2, v11
	s_nop 1
	v_cndmask_b32_e32 v2, v2, v12, vcc
	v_xor_b32_e32 v2, v2, v3
	v_sub_u32_e32 v2, v2, v3
	v_add_u32_e32 v10, v10, v2
; #define PG8_LAS __attribute__((address_space(3)))
;     __host__ __device__ __forceinline__ bool next(int i, Unit& u) const {
;         const long L = (long)i * G + c; if (L >= nwg) return false;
;         int wgid = (int)L; { const int q = nwg / NXCD, r = nwg % NXCD, xcd = wgid % NXCD, off = wgid / NXCD; wgid = (xcd < r ? xcd * (q + 1) : r * (q + 1) + (xcd - r) * q) + off; }
;         const int nig = WGM * nN, gid = wgid / nig, fm = gid * WGM, gsz = (nM - fm) < WGM ? (nM - fm) : WGM;
;         u.pm = fm + ((wgid % nig) % gsz); u.pn = (wgid % nig) / gsz; return true;
;     }
; __device__ __forceinline__ unsigned cvt_pk_bf16(float lo, float hi) { unsigned r; asm volatile("v_cvt_pk_bf16_f32 %0, %1, %2" : "=v"(r) : "v"(lo), "v"(hi)); return r; }
; __device__ __forceinline__ float row_rstd(const float* stats, int row) { const f32x4* sp = (const f32x4*)(stats + (size_t)row * 16); const f32x4 a = sp[0], b = sp[1], c = sp[2], d = sp[3];
;     const float s = ((a[0] + a[1]) + (a[2] + a[3])) + ((b[0] + b[1]) + (b[2] + b[3])) + ((c[0] + c[1]) + (c[2] + c[3])) + ((d[0] + d[1]) + (d[2] + d[3])); return rsqrtf(s * (1.0f / 1024.0f) + 1e-6f); }
; template <class Sched> __device__ __forceinline__ void fill_rstd_table(PG8_LAS float* rsL, const float* stats, const Sched& S, int tid) {
;     Unit u; int n = 0; while (n < 8 && S.next(n, u)) ++n;
;     for (int idx = tid; idx < n * 256; idx += 512) { S.next(idx >> 8, u); rsL[idx] = row_rstd(stats, u.pm * BM + (idx & 255)); }
;     asm volatile("s_waitcnt lgkmcnt(0)" ::: "memory"); __builtin_amdgcn_s_barrier(); asm volatile("" ::: "memory");
.Lfill2_skip2:
	s_or_b64 exec, exec, s[4:5]
	v_lshl_or_b32 v2, v10, 8, v4
	v_ashrrev_i32_e32 v3, 31, v2
	v_lshlrev_b64 v[2:3], 6, v[2:3]
	v_lshl_add_u64 v[2:3], s[14:15], 0, v[2:3]
	global_load_dwordx4 v[60:63], v[2:3], off
	global_load_dwordx4 v[64:67], v[2:3], off offset:16
	global_load_dwordx4 v[68:71], v[2:3], off offset:32
	global_load_dwordx4 v[72:75], v[2:3], off offset:48
	v_add_u32_e32 v9, 0x200, v9
	v_ashrrev_i32_e32 v2, 8, v9
	v_mad_i64_i32 v[2:3], s[4:5], v2, s39, v[0:1]
	v_cmp_gt_i64_e32 vcc, s[18:19], v[2:3]
	s_and_saveexec_b64 s[4:5], vcc
	s_cbranch_execz .Lfill2_skip3
	v_ashrrev_i32_e32 v3, 31, v2
	v_lshrrev_b32_e32 v3, 29, v3
	v_add_u32_e32 v3, v2, v3
	v_ashrrev_i32_e32 v10, 3, v3
	v_and_b32_e32 v3, -8, v3
	v_sub_u32_e32 v2, v2, v3
	v_cmp_gt_i32_e32 vcc, 0, v2
	s_nop 1
	v_cndmask_b32_e32 v3, v7, v8, vcc
	v_mul_lo_u32 v2, v2, v3
	v_add_u32_e32 v2, v2, v10
	v_mul_hi_i32 v3, v2, s22
	v_lshrrev_b32_e32 v10, 31, v3
	v_ashrrev_i32_e32 v3, 5, v3
	v_add_u32_e32 v3, v3, v10
	v_lshlrev_b32_e32 v10, 3, v3
	v_sub_u32_e32 v11, 64, v10
	v_min_i32_e32 v11, 8, v11
	v_sub_u32_e32 v12, 0, v11
	v_max_i32_e32 v11, v11, v12
	v_cvt_f32_u32_e32 v12, v11
	v_mul_lo_u32 v3, v3, s21
	v_sub_u32_e32 v2, v2, v3
	v_sub_u32_e32 v13, 0, v2
	v_rcp_iflag_f32_e32 v12, v12
	v_ashrrev_i32_e32 v3, 31, v2
	v_max_i32_e32 v2, v2, v13
	v_sub_u32_e32 v13, 0, v11
	v_mul_f32_e32 v12, 0x4f7ffffe, v12
	v_cvt_u32_f32_e32 v12, v12
	v_mul_lo_u32 v13, v13, v12
	v_mul_hi_u32 v13, v12, v13
	v_add_u32_e32 v12, v12, v13
	v_mul_hi_u32 v12, v2, v12
	v_mul_lo_u32 v12, v12, v11
	v_sub_u32_e32 v2, v2, v12
	v_sub_u32_e32 v12, v2, v11
	v_cmp_ge_u32_e32 vcc, v2, v11
	s_nop 1
	v_cndmask_b32_e32 v2, v2, v12, vcc
	v_sub_u32_e32 v12, v2, v11
	v_cmp_ge_u32_e32 vcc, v2, v11
	s_nop 1
	v_cndmask_b32_e32 v2, v2, v12, vcc
	v_xor_b32_e32 v2, v2, v3
	v_sub_u32_e32 v2, v2, v3
	v_add_u32_e32 v10, v10, v2
.Lfill2_skip3:
	s_or_b64 exec, exec, s[4:5]
	v_lshl_or_b32 v2, v10, 8, v4
	v_ashrrev_i32_e32 v3, 31, v2
	v_lshlrev_b64 v[2:3], 6, v[2:3]
	v_lshl_add_u64 v[2:3], s[14:15], 0, v[2:3]
	global_load_dwordx4 v[76:79], v[2:3], off
	global_load_dwordx4 v[80:83], v[2:3], off offset:16
	global_load_dwordx4 v[84:87], v[2:3], off offset:32
	global_load_dwordx4 v[88:91], v[2:3], off offset:48
	v_add_u32_e32 v9, 0x200, v9
	s_waitcnt vmcnt(0)
	v_mov_b32_e32 v2, v29
	v_mov_b32_e32 v3, v30
	v_mov_b32_e32 v29, v31
	v_mov_b32_e32 v30, v33
	v_mov_b32_e32 v31, v34
	v_mov_b32_e32 v33, v35
	v_pk_add_f32 v[2:3], v[2:3], v[28:29]
	v_pk_add_f32 v[28:29], v[30:31], v[32:33]
	v_pk_add_f32 v[2:3], v[2:3], v[2:3] op_sel:[0,1] op_sel_hi:[1,0]
	v_pk_add_f32 v[28:29], v[28:29], v[28:29] op_sel:[0,1] op_sel_hi:[1,0]
	v_add_f32_e32 v34, v36, v37
	v_add_f32_e32 v36, v38, v39
	v_mov_b32_e32 v35, v42
	v_mov_b32_e32 v37, v43
	v_mov_b32_e32 v3, v40
	v_mov_b32_e32 v29, v41
	v_pk_add_f32 v[30:31], v[34:35], v[36:37]
	v_pk_add_f32 v[2:3], v[2:3], v[28:29]
	s_nop 0
	v_pk_add_f32 v[2:3], v[2:3], v[30:31]
	s_nop 0
	v_add_f32_e32 v2, v2, v3
	v_fmamk_f32 v2, v2, 0x3a800000, v6
	v_mul_f32_e32 v3, 0x4b800000, v2
	v_cmp_gt_f32_e32 vcc, s23, v2
	s_nop 1
	v_cndmask_b32_e32 v2, v2, v3, vcc
	v_rsq_f32_e32 v2, v2
	s_nop 0
	v_mul_f32_e32 v3, 0x45800000, v2
	v_cndmask_b32_e32 v2, v2, v3, vcc
	ds_write_b32 v5, v2
	v_add_u32_e32 v5, 0x800, v5
	v_mov_b32_e32 v2, v45
	v_mov_b32_e32 v3, v46
	v_mov_b32_e32 v45, v47
	v_mov_b32_e32 v46, v49
	v_mov_b32_e32 v47, v50
	v_mov_b32_e32 v49, v51
	v_pk_add_f32 v[2:3], v[2:3], v[44:45]
	v_pk_add_f32 v[44:45], v[46:47], v[48:49]
	v_pk_add_f32 v[2:3], v[2:3], v[2:3] op_sel:[0,1] op_sel_hi:[1,0]
	v_pk_add_f32 v[44:45], v[44:45], v[44:45] op_sel:[0,1] op_sel_hi:[1,0]
	v_add_f32_e32 v50, v52, v53
	v_add_f32_e32 v52, v54, v55
	v_mov_b32_e32 v51, v58
	v_mov_b32_e32 v53, v59
	v_mov_b32_e32 v3, v56
	v_mov_b32_e32 v45, v57
	v_pk_add_f32 v[46:47], v[50:51], v[52:53]
	v_pk_add_f32 v[2:3], v[2:3], v[44:45]
	s_nop 0
	v_pk_add_f32 v[2:3], v[2:3], v[46:47]
	s_nop 0
	v_add_f32_e32 v2, v2, v3
	v_fmamk_f32 v2, v2, 0x3a800000, v6
	v_mul_f32_e32 v3, 0x4b800000, v2
	v_cmp_gt_f32_e32 vcc, s23, v2
	s_nop 1
	v_cndmask_b32_e32 v2, v2, v3, vcc
	v_rsq_f32_e32 v2, v2
	s_nop 0
	v_mul_f32_e32 v3, 0x45800000, v2
	v_cndmask_b32_e32 v2, v2, v3, vcc
	ds_write_b32 v5, v2
	v_add_u32_e32 v5, 0x800, v5
	v_mov_b32_e32 v2, v61
	v_mov_b32_e32 v3, v62
	v_mov_b32_e32 v61, v63
	v_mov_b32_e32 v62, v65
	v_mov_b32_e32 v63, v66
	v_mov_b32_e32 v65, v67
	v_pk_add_f32 v[2:3], v[2:3], v[60:61]
	v_pk_add_f32 v[60:61], v[62:63], v[64:65]
	v_pk_add_f32 v[2:3], v[2:3], v[2:3] op_sel:[0,1] op_sel_hi:[1,0]
	v_pk_add_f32 v[60:61], v[60:61], v[60:61] op_sel:[0,1] op_sel_hi:[1,0]
	v_add_f32_e32 v66, v68, v69
	v_add_f32_e32 v68, v70, v71
	v_mov_b32_e32 v67, v74
	v_mov_b32_e32 v69, v75
	v_mov_b32_e32 v3, v72
	v_mov_b32_e32 v61, v73
	v_pk_add_f32 v[62:63], v[66:67], v[68:69]
	v_pk_add_f32 v[2:3], v[2:3], v[60:61]
	s_nop 0
	v_pk_add_f32 v[2:3], v[2:3], v[62:63]
	s_nop 0
	v_add_f32_e32 v2, v2, v3
	v_fmamk_f32 v2, v2, 0x3a800000, v6
	v_mul_f32_e32 v3, 0x4b800000, v2
	v_cmp_gt_f32_e32 vcc, s23, v2
	s_nop 1
	v_cndmask_b32_e32 v2, v2, v3, vcc
	v_rsq_f32_e32 v2, v2
	s_nop 0
	v_mul_f32_e32 v3, 0x45800000, v2
	v_cndmask_b32_e32 v2, v2, v3, vcc
	ds_write_b32 v5, v2
	v_add_u32_e32 v5, 0x800, v5
	v_mov_b32_e32 v2, v77
	v_mov_b32_e32 v3, v78
	v_mov_b32_e32 v77, v79
	v_mov_b32_e32 v78, v81
	v_mov_b32_e32 v79, v82
	v_mov_b32_e32 v81, v83
	v_pk_add_f32 v[2:3], v[2:3], v[76:77]
	v_pk_add_f32 v[76:77], v[78:79], v[80:81]
	v_pk_add_f32 v[2:3], v[2:3], v[2:3] op_sel:[0,1] op_sel_hi:[1,0]
	v_pk_add_f32 v[76:77], v[76:77], v[76:77] op_sel:[0,1] op_sel_hi:[1,0]
	v_add_f32_e32 v82, v84, v85
	v_add_f32_e32 v84, v86, v87
	v_mov_b32_e32 v83, v90
	v_mov_b32_e32 v85, v91
	v_mov_b32_e32 v3, v88
	v_mov_b32_e32 v77, v89
	v_pk_add_f32 v[78:79], v[82:83], v[84:85]
	v_pk_add_f32 v[2:3], v[2:3], v[76:77]
	s_nop 0
	v_pk_add_f32 v[2:3], v[2:3], v[78:79]
	s_nop 0
	v_add_f32_e32 v2, v2, v3
	v_fmamk_f32 v2, v2, 0x3a800000, v6
	v_mul_f32_e32 v3, 0x4b800000, v2
	v_cmp_gt_f32_e32 vcc, s23, v2
	s_nop 1
	v_cndmask_b32_e32 v2, v2, v3, vcc
	v_rsq_f32_e32 v2, v2
	s_nop 0
	v_mul_f32_e32 v3, 0x45800000, v2
	v_cndmask_b32_e32 v2, v2, v3, vcc
	ds_write_b32 v5, v2
	v_add_u32_e32 v5, 0x800, v5

; #define PG8_LAS __attribute__((address_space(3)))
;     __host__ __device__ __forceinline__ bool next(int i, Unit& u) const {
;         const long L = (long)i * G + c; if (L >= nwg) return false;
;         int wgid = (int)L; { const int q = nwg / NXCD, r = nwg % NXCD, xcd = wgid % NXCD, off = wgid / NXCD; wgid = (xcd < r ? xcd * (q + 1) : r * (q + 1) + (xcd - r) * q) + off; }
;         const int nig = WGM * nN, gid = wgid / nig, fm = gid * WGM, gsz = (nM - fm) < WGM ? (nM - fm) : WGM;
;         u.pm = fm + ((wgid % nig) % gsz); u.pn = (wgid % nig) / gsz; return true;
;     }
; __device__ __forceinline__ unsigned cvt_pk_bf16(float lo, float hi) { unsigned r; asm volatile("v_cvt_pk_bf16_f32 %0, %1, %2" : "=v"(r) : "v"(lo), "v"(hi)); return r; }
; __device__ __forceinline__ float row_rstd(const float* stats, int row) { const f32x4* sp = (const f32x4*)(stats + (size_t)row * 16); const f32x4 a = sp[0], b = sp[1], c = sp[2], d = sp[3];
;     const float s = ((a[0] + a[1]) + (a[2] + a[3])) + ((b[0] + b[1]) + (b[2] + b[3])) + ((c[0] + c[1]) + (c[2] + c[3])) + ((d[0] + d[1]) + (d[2] + d[3])); return rsqrtf(s * (1.0f / 1024.0f) + 1e-6f); }
; template <class Sched> __device__ __forceinline__ void fill_rstd_table(PG8_LAS float* rsL, const float* stats, const Sched& S, int tid) {
;     Unit u; int n = 0; while (n < 8 && S.next(n, u)) ++n;
;     for (int idx = tid; idx < n * 256; idx += 512) { S.next(idx >> 8, u); rsL[idx] = row_rstd(stats, u.pm * BM + (idx & 255)); }
;     asm volatile("s_waitcnt lgkmcnt(0)" ::: "memory"); __builtin_amdgcn_s_barrier(); asm volatile("" ::: "memory");
.LBB0_2012:
	s_waitcnt lgkmcnt(0)
	s_add_u32 s10, s10, s14
	s_addc_u32 s11, s11, 0
	v_cmp_gt_i32_e32 vcc, s20, v154
	s_and_saveexec_b64 s[12:13], vcc
	s_cbranch_execz .LBB0_2017
	s_add_u32 s14, s10, 0x400000
	v_lshl_add_u32 v0, v154, 2, 0
	s_addc_u32 s15, s11, 0
	v_and_b32_e32 v4, 0xff, v154
	v_add_u32_e32 v5, 0x22000, v0
	s_mov_b64 s[16:17], 0
	v_mov_b32_e32 v10, s18
	v_mov_b64_e32 v[0:1], s[8:9]
	s_mov_b64 s[18:19], 0x580
	s_movk_i32 s21, 0xb0
	s_mov_b32 s22, 0x2e8ba2e9
	v_mov_b32_e32 v6, 0x358637bd
	s_mov_b32 s23, 0x800000
	v_mov_b32_e32 v7, 0xb0
	v_mov_b32_e32 v8, 0xb1
	v_mov_b32_e32 v9, v154
	v_ashrrev_i32_e32 v2, 8, v9
	v_mad_i64_i32 v[2:3], s[4:5], v2, s39, v[0:1]
	v_cmp_gt_i64_e32 vcc, s[18:19], v[2:3]
	s_and_saveexec_b64 s[4:5], vcc
	s_cbranch_execz .Lfill5_skip0
	v_ashrrev_i32_e32 v3, 31, v2
	v_lshrrev_b32_e32 v3, 29, v3
	v_add_u32_e32 v3, v2, v3
	v_ashrrev_i32_e32 v10, 3, v3
	v_and_b32_e32 v3, -8, v3
	v_sub_u32_e32 v2, v2, v3
	v_cmp_gt_i32_e32 vcc, 0, v2
	s_nop 1
	v_cndmask_b32_e32 v3, v7, v8, vcc
	v_mul_lo_u32 v2, v2, v3
	v_add_u32_e32 v2, v2, v10
	v_mul_hi_i32 v3, v2, s22
	v_lshrrev_b32_e32 v10, 31, v3
	v_ashrrev_i32_e32 v3, 5, v3
	v_add_u32_e32 v3, v3, v10
	v_lshlrev_b32_e32 v10, 3, v3
	v_sub_u32_e32 v11, 64, v10
	v_min_i32_e32 v11, 8, v11
	v_sub_u32_e32 v12, 0, v11
	v_max_i32_e32 v11, v11, v12
	v_cvt_f32_u32_e32 v12, v11
	v_mul_lo_u32 v3, v3, s21
	v_sub_u32_e32 v2, v2, v3
	v_sub_u32_e32 v13, 0, v2
	v_rcp_iflag_f32_e32 v12, v12
	v_ashrrev_i32_e32 v3, 31, v2
	v_max_i32_e32 v2, v2, v13
	v_sub_u32_e32 v13, 0, v11
	v_mul_f32_e32 v12, 0x4f7ffffe, v12
	v_cvt_u32_f32_e32 v12, v12
	v_mul_lo_u32 v13, v13, v12
	v_mul_hi_u32 v13, v12, v13
	v_add_u32_e32 v12, v12, v13
	v_mul_hi_u32 v12, v2, v12
	v_mul_lo_u32 v12, v12, v11
	v_sub_u32_e32 v2, v2, v12
	v_sub_u32_e32 v12, v2, v11
	v_cmp_ge_u32_e32 vcc, v2, v11
	s_nop 1
	v_cndmask_b32_e32 v2, v2, v12, vcc
	v_sub_u32_e32 v12, v2, v11
	v_cmp_ge_u32_e32 vcc, v2, v11
	s_nop 1
	v_cndmask_b32_e32 v2, v2, v12, vcc
	v_xor_b32_e32 v2, v2, v3
	v_sub_u32_e32 v2, v2, v3
	v_add_u32_e32 v10, v10, v2
